# convT tile loop weight caching and prefetch overlap, with the compiler's carry-chain pad kept
# baseline (speedup 1.0000x reference)
.LBB0_535:
	s_or_b64 exec, exec, s[28:29]
	s_and_b32 s2, s21, 0x3c0
	v_readlane_b32 s52, v253, 7
	v_or_b32_e32 v17, s2, v46
	v_readlane_b32 s66, v253, 21
	v_readlane_b32 s67, v253, 22
	v_lshlrev_b32_e32 v82, 2, v17
	v_mov_b32_e32 v83, v16
	s_mov_b64 s[30:31], s[66:67]
	v_lshl_add_u64 v[84:85], s[30:31], 0, v[82:83]
	s_and_b32 s28, s20, 0xffffffc0
	s_cmp_eq_u32 s98, 0
	s_cbranch_scc0 .Lmy_cw_cached
	v_add_co_u32_e32 v86, vcc, 0x3000, v84
	global_load_dword v247, v82, s[48:49]
	global_load_dword v68, v82, s[66:67]
	v_addc_co_u32_e32 v87, vcc, 0, v85, vcc
	global_load_dword v66, v[86:87], off
	v_add_co_u32_e32 v86, vcc, 0x6000, v84
	v_or_b32_e32 v17, 0x1000, v82
	s_nop 0
	v_addc_co_u32_e32 v87, vcc, 0, v85, vcc
	global_load_dword v64, v[86:87], off
	v_add_co_u32_e32 v86, vcc, 0x4000, v84
	global_load_dword v248, v17, s[48:49]
	global_load_dword v62, v17, s[66:67]
	v_addc_co_u32_e32 v87, vcc, 0, v85, vcc
	global_load_dword v60, v[86:87], off
	v_add_co_u32_e32 v86, vcc, 0x7000, v84
	v_or_b32_e32 v17, 0x2000, v82
	s_nop 0
	v_addc_co_u32_e32 v87, vcc, 0, v85, vcc
	v_add_co_u32_e32 v82, vcc, 0x5000, v84
	global_load_dword v58, v[86:87], off
	s_nop 0
	v_addc_co_u32_e32 v83, vcc, 0, v85, vcc
	global_load_dword v249, v17, s[48:49]
	global_load_dword v56, v17, s[66:67]
	global_load_dword v54, v[82:83], off
	v_add_co_u32_e32 v82, vcc, 0x8000, v84
	s_nop 0
	s_nop 0
	v_addc_co_u32_e32 v83, vcc, 0, v85, vcc
	global_load_dword v52, v[82:83], off
	s_mov_b32 s98, 1
	s_waitcnt vmcnt(0)
